# grid barrier poll loops back off longer between polls (s_sleep 16) to cut uncached poll traffic on the shard counters
# baseline (speedup 1.0000x reference)
; #define GAS __attribute__((address_space(1)))
; DI void grid_barrier(unsigned* ctr, const unsigned target) {
;     ...
;   if (threadIdx.x == 0) {
;     __builtin_amdgcn_fence(__ATOMIC_RELEASE, "agent");
;     asm volatile("s_waitcnt vmcnt(0)" ::: "memory");
;     __hip_atomic_fetch_add((GAS unsigned*)ctr, 1u, __ATOMIC_RELAXED, __HIP_MEMORY_SCOPE_AGENT);
;     while (__hip_atomic_load((GAS unsigned*)ctr, __ATOMIC_RELAXED, __HIP_MEMORY_SCOPE_AGENT) < target) __builtin_amdgcn_s_sleep(1);
;     __builtin_amdgcn_fence(__ATOMIC_ACQUIRE, "agent");
.LBB0_141:
	s_sleep 16
	global_load_dword v0, v3, s[8:9] sc1
	s_waitcnt vmcnt(0)
	v_cmp_gt_u32_e32 vcc, s3, v0
	s_cbranch_vccnz .LBB0_141

; #define GAS __attribute__((address_space(1)))
; DI void grid_barrier(unsigned* ctr, const unsigned target) {
;     ...
;   if (threadIdx.x == 0) {
;     __builtin_amdgcn_fence(__ATOMIC_RELEASE, "agent");
;     asm volatile("s_waitcnt vmcnt(0)" ::: "memory");
;     __hip_atomic_fetch_add((GAS unsigned*)ctr, 1u, __ATOMIC_RELAXED, __HIP_MEMORY_SCOPE_AGENT);
;     while (__hip_atomic_load((GAS unsigned*)ctr, __ATOMIC_RELAXED, __HIP_MEMORY_SCOPE_AGENT) < target) __builtin_amdgcn_s_sleep(1);
;     __builtin_amdgcn_fence(__ATOMIC_ACQUIRE, "agent");
.LBB0_174:
	s_sleep 16
	global_load_dword v0, v3, s[8:9] sc1
	s_waitcnt vmcnt(0)
	v_cmp_gt_u32_e32 vcc, s2, v0
	s_cbranch_vccnz .LBB0_174

; #define GAS __attribute__((address_space(1)))
; DI void grid_barrier(unsigned* ctr, const unsigned target) {
;     ...
;   if (threadIdx.x == 0) {
;     __builtin_amdgcn_fence(__ATOMIC_RELEASE, "agent");
;     asm volatile("s_waitcnt vmcnt(0)" ::: "memory");
;     __hip_atomic_fetch_add((GAS unsigned*)ctr, 1u, __ATOMIC_RELAXED, __HIP_MEMORY_SCOPE_AGENT);
;     while (__hip_atomic_load((GAS unsigned*)ctr, __ATOMIC_RELAXED, __HIP_MEMORY_SCOPE_AGENT) < target) __builtin_amdgcn_s_sleep(1);
;     __builtin_amdgcn_fence(__ATOMIC_ACQUIRE, "agent");
.LBB0_510:
	s_sleep 16
	global_load_dword v0, v3, s[6:7] sc1
	s_waitcnt vmcnt(0)
	v_cmp_gt_u32_e32 vcc, s2, v0
	s_cbranch_vccnz .LBB0_510

; #define GAS __attribute__((address_space(1)))
; DI void grid_barrier(unsigned* ctr, const unsigned target) {
;     ...
;   if (threadIdx.x == 0) {
;     __builtin_amdgcn_fence(__ATOMIC_RELEASE, "agent");
;     asm volatile("s_waitcnt vmcnt(0)" ::: "memory");
;     __hip_atomic_fetch_add((GAS unsigned*)ctr, 1u, __ATOMIC_RELAXED, __HIP_MEMORY_SCOPE_AGENT);
;     while (__hip_atomic_load((GAS unsigned*)ctr, __ATOMIC_RELAXED, __HIP_MEMORY_SCOPE_AGENT) < target) __builtin_amdgcn_s_sleep(1);
;     __builtin_amdgcn_fence(__ATOMIC_ACQUIRE, "agent");
.LBB0_543:
	s_sleep 16
	global_load_dword v0, v3, s[4:5] sc1
	s_waitcnt vmcnt(0)
	v_cmp_gt_u32_e32 vcc, s3, v0
	s_cbranch_vccnz .LBB0_543

; #define GAS __attribute__((address_space(1)))
; DI void grid_barrier(unsigned* ctr, const unsigned target) {
;     ...
;   if (threadIdx.x == 0) {
;     __builtin_amdgcn_fence(__ATOMIC_RELEASE, "agent");
;     asm volatile("s_waitcnt vmcnt(0)" ::: "memory");
;     __hip_atomic_fetch_add((GAS unsigned*)ctr, 1u, __ATOMIC_RELAXED, __HIP_MEMORY_SCOPE_AGENT);
;     while (__hip_atomic_load((GAS unsigned*)ctr, __ATOMIC_RELAXED, __HIP_MEMORY_SCOPE_AGENT) < target) __builtin_amdgcn_s_sleep(1);
;     __builtin_amdgcn_fence(__ATOMIC_ACQUIRE, "agent");
.LBB0_570:
	s_sleep 16
	global_load_dword v0, v3, s[4:5] sc1
	s_waitcnt vmcnt(0)
	v_cmp_gt_u32_e32 vcc, s2, v0
	s_cbranch_vccnz .LBB0_570
